# row-norm rebalance v2 + next-row prefetch in P7 and P11
# speedup vs baseline: 1.0149x; 1.0029x over previous
.LBB0_1005:
	v_readlane_b32 s2, v248, 0
	v_readlane_b32 s3, v248, 1
	s_cmp_lt_i32 s2, 8
	s_cselect_b64 s[2:3], -1, 0
	s_and_b64 s[2:3], s[2:3], s[0:1]
	s_andn2_b64 vcc, exec, s[2:3]
	s_cbranch_vccnz .LBB0_1019
	v_lshl_or_b32 v34, s82, 3, v210
	s_movk_i32 s0, 0x4080
	v_cmp_gt_i32_e32 vcc, s0, v34
	s_and_saveexec_b64 s[4:5], vcc
	s_cbranch_execz .LBB0_1018
	v_lshlrev_b32_e32 v1, 2, v0
	v_and_b32_e32 v18, 0xfc, v1
	v_lshlrev_b32_e32 v36, 2, v18
	v_mbcnt_lo_u32_b32 v1, -1, 0
	v_mbcnt_hi_u32_b32 v19, -1, v1
	v_and_b32_e32 v22, 64, v19
	v_xor_b32_e32 v1, 1, v19
	v_add_u32_e32 v22, 64, v22
	v_cmp_lt_i32_e32 vcc, v1, v22
	v_xor_b32_e32 v23, 2, v19
	v_readlane_b32 s8, v248, 2
	v_cndmask_b32_e32 v1, v19, v1, vcc
	v_cmp_lt_i32_e32 vcc, v23, v22
	v_mov_b32_e32 v37, 0
	v_readlane_b32 s9, v248, 3
	v_cndmask_b32_e32 v23, v19, v23, vcc
	v_lshlrev_b32_e32 v46, 2, v23
	v_xor_b32_e32 v23, 4, v19
	v_cmp_lt_i32_e32 vcc, v23, v22
	v_readlane_b32 s10, v248, 4
	v_readlane_b32 s11, v248, 5
	v_cndmask_b32_e32 v23, v19, v23, vcc
	v_lshlrev_b32_e32 v47, 2, v23
	v_xor_b32_e32 v23, 8, v19
	v_cmp_lt_i32_e32 vcc, v23, v22
	s_cmp_lg_u64 s[10:11], 0
	v_lshl_add_u64 v[20:21], s[94:95], 0, v[36:37]
	v_cndmask_b32_e32 v23, v19, v23, vcc
	v_lshlrev_b32_e32 v48, 2, v23
	v_xor_b32_e32 v23, 16, v19
	v_cmp_lt_i32_e32 vcc, v23, v22
	s_mov_b64 s[8:9], 0xb3d6400
	v_lshl_add_u64 v[40:41], s[92:93], 0, v[36:37]
	v_cndmask_b32_e32 v23, v19, v23, vcc
	v_lshlrev_b32_e32 v49, 2, v23
	v_xor_b32_e32 v23, 32, v19
	v_lshlrev_b32_e32 v36, 1, v18
	v_cmp_lt_i32_e32 vcc, v23, v22
	s_cselect_b64 s[0:1], -1, 0
	v_lshl_add_u64 v[38:39], v[20:21], 0, s[8:9]
	v_lshl_add_u64 v[20:21], s[94:95], 0, v[36:37]
	s_mov_b64 s[8:9], 0xbf0cc00
	v_cndmask_b32_e32 v19, v19, v23, vcc
	v_readlane_b32 s12, v248, 6
	v_readlane_b32 s13, v248, 7
	v_readlane_b32 s14, v248, 8
	v_readlane_b32 s15, v248, 9
	v_readlane_b32 s16, v248, 10
	v_readlane_b32 s17, v248, 11
	v_readlane_b32 s18, v248, 12
	v_readlane_b32 s19, v248, 13
	v_readlane_b32 s20, v248, 14
	v_readlane_b32 s21, v248, 15
	v_readlane_b32 s22, v248, 16
	v_lshl_add_u64 v[42:43], v[20:21], 0, s[8:9]
	v_lshlrev_b32_e32 v50, 2, v19
	s_mov_b64 s[8:9], 0x1f80000
	v_cndmask_b32_e64 v19, 0, 1, s[0:1]
	s_mov_b64 s[6:7], 0
	v_lshlrev_b32_e32 v1, 2, v1
	v_lshl_add_u64 v[44:45], v[20:21], 0, s[8:9]
	s_waitcnt lgkmcnt(0)
	s_lshl_b32 s12, s96, 3
	s_movk_i32 s13, 0x3fff
	v_cmp_ne_u32_e64 s[0:1], 1, v19
	v_lshlrev_b32_e32 v36, 2, v18
	s_mov_b32 s14, 0x80000
	s_mov_b32 s15, 0x100000
	s_mov_b32 s16, 0x180000
	s_mov_b32 s17, 0x200000
	s_mov_b32 s18, 0x280000
	s_mov_b32 s19, 0x300000
	s_mov_b32 s20, 0x380000
	v_mov_b32_e32 v51, 0x3727c5ac
	s_mov_b32 s21, 0x800000
	s_movk_i32 s22, 0x407f
	v_readlane_b32 s23, v248, 17
	v_and_b32_e32 v228, 15, v34
	v_add_u32_e32 v224, 0x4000, v34
	v_mov_b32_e32 v225, 0x7fffffff
	v_mov_b32_e32 v226, -1
	v_mov_b32_e32 v227, 0x7fffffff
	v_add_u32_e32 v229, 0x3000, v34
	v_lshrrev_b32_e32 v230, 4, v34
	v_add_u32_e32 v230, 0x4000, v230
	v_cmp_eq_u32_e32 vcc, 0, v228
	s_nop 1
	v_cndmask_b32_e32 v224, v224, v229, vcc
	v_cndmask_b32_e32 v225, v225, v230, vcc
	v_add_u32_e32 v229, 0x2ff8, v34
	v_add_u32_e32 v230, 0x800, v229
	v_cmp_eq_u32_e32 vcc, 8, v228
	s_nop 1
	v_cndmask_b32_e32 v225, v225, v229, vcc
	v_cndmask_b32_e32 v226, v226, v230, vcc
	v_add_u32_e32 v229, 0x37fc, v34
	v_add_u32_e32 v230, 0x800, v229
	v_cmp_eq_u32_e32 vcc, 4, v228
	s_nop 1
	v_cndmask_b32_e32 v225, v225, v229, vcc
	v_cndmask_b32_e32 v226, v226, v230, vcc
	v_mov_b32_e32 v222, v34
	v_mov_b32_e32 v223, 0
	v_lshlrev_b64 v[220:221], 11, v[222:223]
	v_lshl_add_u64 v[220:221], v[42:43], 0, v[220:221]
	global_load_dwordx2 v[212:213], v[220:221], off
	global_load_dwordx2 v[214:215], v[220:221], off offset:512
	global_load_dwordx2 v[216:217], v[220:221], off offset:1024
	global_load_dwordx2 v[218:219], v[220:221], off offset:1536
	global_load_dwordx4 v[2:5], v36, s[80:81]
	global_load_dwordx4 v[6:9], v36, s[80:81] offset:1024
	global_load_dwordx4 v[10:13], v36, s[80:81] offset:2048
	global_load_dwordx4 v[14:17], v36, s[80:81] offset:3072
	s_branch .LBB0_1009

.LBB0_1262:
	v_readlane_b32 s2, v248, 0
	v_readlane_b32 s3, v248, 1
	s_cmp_lt_i32 s2, 12
	s_cselect_b64 s[2:3], -1, 0
	s_and_b64 s[0:1], s[2:3], s[0:1]
	s_andn2_b64 vcc, exec, s[0:1]
	s_cbranch_vccnz .LBB0_1270
	v_lshl_or_b32 v16, s82, 3, v210
	s_movk_i32 s0, 0x4080
	v_cmp_gt_i32_e32 vcc, s0, v16
	s_and_saveexec_b64 s[0:1], vcc
	s_cbranch_execz .LBB0_1270
	v_lshlrev_b32_e32 v0, 2, v0
	v_and_b32_e32 v17, 0xfc, v0
	v_lshlrev_b32_e32 v18, 2, v17
	v_lshlrev_b32_e32 v22, 1, v17
	v_mbcnt_lo_u32_b32 v17, -1, 0
	v_mbcnt_hi_u32_b32 v17, -1, v17
	v_and_b32_e32 v25, 64, v17
	v_xor_b32_e32 v24, 1, v17
	v_add_u32_e32 v25, 64, v25
	v_cmp_lt_i32_e32 vcc, v24, v25
	v_mov_b32_e32 v19, 0
	v_lshl_add_u64 v[20:21], s[94:95], 0, v[18:19]
	v_cndmask_b32_e32 v24, v17, v24, vcc
	v_lshlrev_b32_e32 v44, 2, v24
	v_xor_b32_e32 v24, 2, v17
	v_cmp_lt_i32_e32 vcc, v24, v25
	s_mov_b64 s[0:1], 0xb3d6400
	v_mov_b32_e32 v23, v19
	v_cndmask_b32_e32 v24, v17, v24, vcc
	v_lshlrev_b32_e32 v45, 2, v24
	v_xor_b32_e32 v24, 4, v17
	v_cmp_lt_i32_e32 vcc, v24, v25
	v_lshl_add_u64 v[20:21], v[20:21], 0, s[0:1]
	v_lshl_add_u64 v[22:23], s[94:95], 0, v[22:23]
	v_cndmask_b32_e32 v24, v17, v24, vcc
	v_lshlrev_b32_e32 v46, 2, v24
	v_xor_b32_e32 v24, 8, v17
	v_cmp_lt_i32_e32 vcc, v24, v25
	s_mov_b64 s[0:1], 0x1f80000
	v_lshl_add_u64 v[22:23], v[22:23], 0, s[0:1]
	v_cndmask_b32_e32 v24, v17, v24, vcc
	v_lshlrev_b32_e32 v47, 2, v24
	v_xor_b32_e32 v24, 16, v17
	v_cmp_lt_i32_e32 vcc, v24, v25
	s_waitcnt lgkmcnt(0)
	s_lshl_b32 s4, s96, 3
	s_mov_b64 s[0:1], 0
	v_cndmask_b32_e32 v24, v17, v24, vcc
	v_lshlrev_b32_e32 v48, 2, v24
	v_xor_b32_e32 v24, 32, v17
	v_cmp_lt_i32_e32 vcc, v24, v25
	s_movk_i32 s5, 0x3fff
	v_mov_b32_e32 v50, 0x3727c5ac
	v_cndmask_b32_e32 v17, v17, v24, vcc
	v_lshlrev_b32_e32 v49, 2, v17
	v_lshl_add_u64 v[24:25], s[92:93], 0, v[18:19]
	s_mov_b32 s6, 0x800000
	s_movk_i32 s7, 0x407f
	v_and_b32_e32 v232, 15, v16
	v_add_u32_e32 v228, 0x4000, v16
	v_mov_b32_e32 v229, 0x7fffffff
	v_mov_b32_e32 v230, -1
	v_mov_b32_e32 v231, 0x7fffffff
	v_add_u32_e32 v233, 0x3000, v16
	v_lshrrev_b32_e32 v234, 4, v16
	v_add_u32_e32 v234, 0x4000, v234
	v_cmp_eq_u32_e32 vcc, 0, v232
	s_nop 1
	v_cndmask_b32_e32 v228, v228, v233, vcc
	v_cndmask_b32_e32 v229, v229, v234, vcc
	v_add_u32_e32 v233, 0x2ff8, v16
	v_add_u32_e32 v234, 0x800, v233
	v_cmp_eq_u32_e32 vcc, 8, v232
	s_nop 1
	v_cndmask_b32_e32 v229, v229, v233, vcc
	v_cndmask_b32_e32 v230, v230, v234, vcc
	v_add_u32_e32 v233, 0x37fc, v16
	v_add_u32_e32 v234, 0x800, v233
	v_cmp_eq_u32_e32 vcc, 4, v232
	s_nop 1
	v_cndmask_b32_e32 v229, v229, v233, vcc
	v_cndmask_b32_e32 v230, v230, v234, vcc
	v_mov_b32_e32 v234, v16
	v_mov_b32_e32 v235, 0
	v_lshlrev_b64 v[244:245], 11, v[234:235]
	v_lshl_add_u64 v[244:245], v[22:23], 0, v[244:245]
	global_load_dwordx2 v[236:237], v[244:245], off
	global_load_dwordx2 v[238:239], v[244:245], off offset:512
	global_load_dwordx2 v[240:241], v[244:245], off offset:1024
	global_load_dwordx2 v[242:243], v[244:245], off offset:1536
	global_load_dwordx4 v[0:3], v18, s[90:91]
	global_load_dwordx4 v[4:7], v18, s[90:91] offset:1024
	global_load_dwordx4 v[8:11], v18, s[90:91] offset:2048
	global_load_dwordx4 v[12:15], v18, s[90:91] offset:3072
	s_branch .LBB0_1266
